# gate/up epilogue: per element pair the two scalar multiplies by -log2e and the two +1.0 adds become one v_pk_mul_f32 / v_pk_add_f32 (same f32 operations)
# baseline (speedup 1.0000x reference)
.Lp8_rr_join:
	s_mov_b32 s88, 0xbfb8aa3b
	v_mov_b32_e32 v186, v203
	v_mov_b32_e32 v187, v204
	v_mov_b32_e32 v203, v205
	v_mov_b32_e32 v190, v207
	v_mov_b32_e32 v191, v208
	v_mov_b32_e32 v207, v209
	v_pk_add_f32 v[186:187], v[186:187], v[202:203]
	v_pk_add_f32 v[190:191], v[190:191], v[206:207]
	v_mov_b32_e32 v203, v186
	v_mov_b32_e32 v202, v190
	v_mov_b32_e32 v186, v191
	v_pk_add_f32 v[186:187], v[202:203], v[186:187]
	ds_bpermute_b32 v191, v167, v187
	ds_bpermute_b32 v190, v167, v186
	v_cndmask_b32_e32 v165, v239, v165, vcc
	v_lshlrev_b32_e32 v165, 2, v165
	s_waitcnt lgkmcnt(0)
	v_pk_add_f32 v[186:187], v[186:187], v[190:191]
	ds_bpermute_b32 v191, v165, v187
	ds_bpermute_b32 v190, v165, v186
	s_waitcnt lgkmcnt(0)
	v_pk_add_f32 v[190:191], v[186:187], v[190:191]
	v_mov_b64_e32 v[186:187], s[80:81]
	v_pk_fma_f32 v[190:191], v[190:191], s[78:79], v[186:187] op_sel_hi:[1,0,0]
	s_nop 0
	v_mul_f32_e32 v169, 0x4b800000, v191
	v_cmp_gt_f32_e64 s[8:9], s66, v191
	v_cmp_gt_f32_e32 vcc, s66, v190
	s_nop 0
	v_cndmask_b32_e64 v169, v191, v169, s[8:9]
	v_rsq_f32_e32 v169, v169
	v_mov_b32_e32 v191, v150
	v_mov_b32_e32 v150, v145
	v_mov_b32_e32 v145, v147
	v_mul_f32_e32 v171, 0x45800000, v169
	v_cndmask_b32_e64 v184, v169, v171, s[8:9]
	v_mul_f32_e32 v169, 0x4b800000, v190
	v_cndmask_b32_e32 v169, v190, v169, vcc
	v_mov_b32_e32 v190, v149
	v_mov_b32_e32 v149, v151
	v_mov_b32_e32 v151, v146
	v_pk_add_f32 v[148:149], v[190:191], v[148:149]
	v_pk_add_f32 v[144:145], v[150:151], v[144:145]
	v_mov_b32_e32 v147, v148
	v_mov_b32_e32 v146, v144
	v_mov_b32_e32 v148, v145
	v_pk_add_f32 v[144:145], v[146:147], v[148:149]
	ds_bpermute_b32 v147, v167, v145
	ds_bpermute_b32 v146, v167, v144
	v_mov_b32_e32 v148, v141
	v_mov_b32_e32 v149, v142
	v_mov_b32_e32 v141, v143
	v_mov_b32_e32 v142, v137
	v_mov_b32_e32 v143, v138
	v_mov_b32_e32 v137, v139
	v_pk_add_f32 v[140:141], v[148:149], v[140:141]
	v_pk_add_f32 v[136:137], v[142:143], v[136:137]
	s_waitcnt lgkmcnt(0)
	v_pk_add_f32 v[144:145], v[144:145], v[146:147]
	v_mov_b32_e32 v138, v136
	v_mov_b32_e32 v139, v140
	v_mov_b32_e32 v140, v137
	ds_bpermute_b32 v147, v165, v145
	ds_bpermute_b32 v146, v165, v144
	v_pk_add_f32 v[136:137], v[138:139], v[140:141]
	ds_bpermute_b32 v139, v167, v137
	ds_bpermute_b32 v138, v167, v136
	v_mov_b32_e32 v140, v133
	v_mov_b32_e32 v141, v134
	v_mov_b32_e32 v133, v135
	v_mov_b32_e32 v134, v129
	v_mov_b32_e32 v135, v130
	v_mov_b32_e32 v129, v131
	s_waitcnt lgkmcnt(2)
	v_pk_add_f32 v[144:145], v[144:145], v[146:147]
	v_pk_add_f32 v[132:133], v[140:141], v[132:133]
	v_pk_add_f32 v[128:129], v[134:135], v[128:129]
	v_pk_fma_f32 v[144:145], v[144:145], s[78:79], v[186:187] op_sel_hi:[1,0,0]
	s_waitcnt lgkmcnt(0)
	v_pk_add_f32 v[136:137], v[136:137], v[138:139]
	v_mov_b32_e32 v130, v128
	v_mov_b32_e32 v131, v132
	v_mov_b32_e32 v132, v129
	v_mul_f32_e32 v146, 0x4b800000, v145
	v_cmp_gt_f32_e64 s[8:9], s66, v145
	ds_bpermute_b32 v139, v165, v137
	ds_bpermute_b32 v138, v165, v136
	v_pk_add_f32 v[128:129], v[130:131], v[132:133]
	v_cndmask_b32_e64 v145, v145, v146, s[8:9]
	ds_bpermute_b32 v131, v167, v129
	ds_bpermute_b32 v130, v167, v128
	v_rsq_f32_e32 v169, v169
	v_rsq_f32_e32 v145, v145
	s_waitcnt lgkmcnt(2)
	v_pk_add_f32 v[136:137], v[136:137], v[138:139]
	v_pk_mul_f32 v[124:125], v[124:125], v[184:185] op_sel_hi:[1,0]
	v_mul_f32_e32 v171, 0x45800000, v169
	v_mul_f32_e32 v146, 0x45800000, v145
	v_pk_fma_f32 v[136:137], v[136:137], s[78:79], v[186:187] op_sel_hi:[1,0,0]
	s_waitcnt lgkmcnt(0)
	v_pk_add_f32 v[128:129], v[128:129], v[130:131]
	v_cndmask_b32_e32 v182, v169, v171, vcc
	v_cmp_gt_f32_e32 vcc, s66, v144
	v_cndmask_b32_e64 v146, v145, v146, s[8:9]
	v_mul_f32_e32 v145, 0x4b800000, v144
	v_mul_f32_e32 v138, 0x4b800000, v137
	v_cmp_gt_f32_e64 s[8:9], s66, v137
	ds_bpermute_b32 v131, v165, v129
	ds_bpermute_b32 v130, v165, v128
	v_cndmask_b32_e32 v144, v144, v145, vcc
	v_cndmask_b32_e64 v137, v137, v138, s[8:9]
	v_rsq_f32_e32 v144, v144
	v_rsq_f32_e32 v137, v137
	s_waitcnt lgkmcnt(0)
	v_pk_add_f32 v[128:129], v[128:129], v[130:131]
	v_pk_mul_f32 v[120:121], v[120:121], v[184:185] op_sel_hi:[1,0]
	v_mul_f32_e32 v145, 0x45800000, v144
	v_mul_f32_e32 v138, 0x45800000, v137
	v_pk_fma_f32 v[128:129], v[128:129], s[78:79], v[186:187] op_sel_hi:[1,0,0]
	v_cndmask_b32_e32 v144, v144, v145, vcc
	v_cmp_gt_f32_e32 vcc, s66, v136
	v_cndmask_b32_e64 v138, v137, v138, s[8:9]
	v_mul_f32_e32 v137, 0x4b800000, v136
	v_mul_f32_e32 v130, 0x4b800000, v129
	v_cmp_gt_f32_e64 s[8:9], s66, v129
	v_cndmask_b32_e32 v136, v136, v137, vcc
	v_rsq_f32_e32 v136, v136
	v_cndmask_b32_e64 v129, v129, v130, s[8:9]
	v_rsq_f32_e32 v129, v129
	v_pk_mul_f32 v[122:123], v[122:123], v[184:185] op_sel_hi:[1,0]
	v_mul_f32_e32 v137, 0x45800000, v136
	v_cndmask_b32_e32 v136, v136, v137, vcc
	v_mul_f32_e32 v130, 0x45800000, v129
	v_cmp_gt_f32_e32 vcc, s66, v128
	v_cndmask_b32_e64 v130, v129, v130, s[8:9]
	v_mul_f32_e32 v129, 0x4b800000, v128
	v_cndmask_b32_e32 v128, v128, v129, vcc
	v_rsq_f32_e32 v128, v128
	v_pk_mul_f32 v[116:117], v[116:117], v[184:185] op_sel_hi:[1,0]
	v_pk_mul_f32 v[112:113], v[112:113], v[184:185] op_sel_hi:[1,0]
	v_pk_mul_f32 v[114:115], v[114:115], v[184:185] op_sel_hi:[1,0]
	v_mul_f32_e32 v129, 0x45800000, v128
	v_cndmask_b32_e32 v128, v128, v129, vcc
	v_mul_f32_e32 v129, 0xbfb8aa3b, v124
	v_exp_f32_e32 v129, v129
	v_pk_mul_f32 v[108:109], v[108:109], v[182:183] op_sel_hi:[1,0]
	v_pk_mul_f32 v[104:105], v[104:105], v[182:183] op_sel_hi:[1,0]
	v_pk_mul_f32 v[106:107], v[106:107], v[182:183] op_sel_hi:[1,0]
	v_add_f32_e32 v129, 1.0, v129
	v_rcp_f32_e32 v132, v129
	v_mul_f32_e32 v129, 0xbfb8aa3b, v125
	v_exp_f32_e32 v129, v129
	v_pk_mul_f32 v[100:101], v[100:101], v[182:183] op_sel_hi:[1,0]
	v_pk_mul_f32 v[96:97], v[96:97], v[182:183] op_sel_hi:[1,0]
	v_pk_mul_f32 v[98:99], v[98:99], v[182:183] op_sel_hi:[1,0]
	v_add_f32_e32 v129, 1.0, v129
	v_rcp_f32_e32 v133, v129
	v_pk_mul_f32 v[92:93], v[92:93], v[146:147] op_sel_hi:[1,0]
	v_pk_mul_f32 v[88:89], v[88:89], v[146:147] op_sel_hi:[1,0]
	v_pk_mul_f32 v[90:91], v[90:91], v[146:147] op_sel_hi:[1,0]
	v_pk_mul_f32 v[124:125], v[124:125], v[132:133]
	v_pk_mul_f32 v[84:85], v[84:85], v[146:147] op_sel_hi:[1,0]
	v_pk_mul_f32 v[120:121], v[120:121], v[124:125]
	v_pk_mul_f32 v[124:125], v[126:127], v[184:185] op_sel_hi:[1,0]
	v_pk_mul_f32 v[80:81], v[80:81], v[146:147] op_sel_hi:[1,0]
	v_pk_mul_f32 v[126:127], v[124:125], s[88:89] op_sel_hi:[1,0]
	v_exp_f32_e32 v126, v126
	v_exp_f32_e32 v127, v127
	v_pk_mul_f32 v[82:83], v[82:83], v[146:147] op_sel_hi:[1,0]
	v_pk_mul_f32 v[76:77], v[76:77], v[144:145] op_sel_hi:[1,0]
	v_pk_add_f32 v[126:127], v[126:127], 1.0 op_sel_hi:[1,0]
	v_rcp_f32_e32 v126, v126
	v_rcp_f32_e32 v127, v127
	v_pk_mul_f32 v[72:73], v[72:73], v[144:145] op_sel_hi:[1,0]
	v_pk_mul_f32 v[74:75], v[74:75], v[144:145] op_sel_hi:[1,0]
	v_pk_mul_f32 v[68:69], v[68:69], v[144:145] op_sel_hi:[1,0]
	v_pk_mul_f32 v[124:125], v[124:125], v[126:127]
	v_pk_mul_f32 v[64:65], v[64:65], v[144:145] op_sel_hi:[1,0]
	v_pk_mul_f32 v[122:123], v[122:123], v[124:125]
	v_pk_mul_f32 v[124:125], v[116:117], s[88:89] op_sel_hi:[1,0]
	v_exp_f32_e32 v124, v124
	v_exp_f32_e32 v125, v125
	v_pk_mul_f32 v[66:67], v[66:67], v[144:145] op_sel_hi:[1,0]
	v_pk_mul_f32 v[60:61], v[60:61], v[138:139] op_sel_hi:[1,0]
	v_pk_add_f32 v[124:125], v[124:125], 1.0 op_sel_hi:[1,0]
	v_rcp_f32_e32 v124, v124
	v_rcp_f32_e32 v125, v125
	v_pk_mul_f32 v[56:57], v[56:57], v[138:139] op_sel_hi:[1,0]
	v_pk_mul_f32 v[58:59], v[58:59], v[138:139] op_sel_hi:[1,0]
	v_pk_mul_f32 v[52:53], v[52:53], v[138:139] op_sel_hi:[1,0]
	v_pk_mul_f32 v[116:117], v[116:117], v[124:125]
	v_pk_mul_f32 v[48:49], v[48:49], v[138:139] op_sel_hi:[1,0]
	v_pk_mul_f32 v[112:113], v[112:113], v[116:117]
	v_pk_mul_f32 v[116:117], v[118:119], v[184:185] op_sel_hi:[1,0]
	v_pk_mul_f32 v[50:51], v[50:51], v[138:139] op_sel_hi:[1,0]
	v_pk_mul_f32 v[118:119], v[116:117], s[88:89] op_sel_hi:[1,0]
	v_exp_f32_e32 v118, v118
	v_exp_f32_e32 v119, v119
	v_pk_mul_f32 v[44:45], v[44:45], v[136:137] op_sel_hi:[1,0]
	v_pk_mul_f32 v[40:41], v[40:41], v[136:137] op_sel_hi:[1,0]
	v_pk_add_f32 v[118:119], v[118:119], 1.0 op_sel_hi:[1,0]
	v_rcp_f32_e32 v118, v118
	v_rcp_f32_e32 v119, v119
	v_pk_mul_f32 v[42:43], v[42:43], v[136:137] op_sel_hi:[1,0]
	v_pk_mul_f32 v[36:37], v[36:37], v[136:137] op_sel_hi:[1,0]
	v_pk_mul_f32 v[32:33], v[32:33], v[136:137] op_sel_hi:[1,0]
	v_pk_mul_f32 v[116:117], v[116:117], v[118:119]
	v_cvt_pk_bf16_f32 v118, v112, v113
	v_pk_mul_f32 v[114:115], v[114:115], v[116:117]
	v_mov_b64_e32 v[112:113], s[12:13]
	v_cvt_pk_bf16_f32 v116, v120, v121
	v_cvt_pk_bf16_f32 v119, v114, v115
	v_mad_i64_i32 v[120:121], s[8:9], v178, s3, v[112:113]
	v_lshlrev_b64 v[114:115], 1, v[180:181]
	v_cvt_pk_bf16_f32 v117, v122, v123
	v_lshl_add_u64 v[120:121], v[120:121], 0, v[114:115]
	global_store_dwordx4 v[120:121], v[116:119], off
	v_pk_mul_f32 v[34:35], v[34:35], v[136:137] op_sel_hi:[1,0]
	v_pk_mul_f32 v[28:29], v[28:29], v[130:131] op_sel_hi:[1,0]
	v_pk_mul_f32 v[116:117], v[108:109], s[88:89] op_sel_hi:[1,0]
	v_exp_f32_e32 v116, v116
	v_exp_f32_e32 v117, v117
	v_pk_mul_f32 v[24:25], v[24:25], v[130:131] op_sel_hi:[1,0]
	v_pk_mul_f32 v[26:27], v[26:27], v[130:131] op_sel_hi:[1,0]
	v_pk_add_f32 v[116:117], v[116:117], 1.0 op_sel_hi:[1,0]
	v_rcp_f32_e32 v116, v116
	v_rcp_f32_e32 v117, v117
	v_pk_mul_f32 v[20:21], v[20:21], v[130:131] op_sel_hi:[1,0]
	v_pk_mul_f32 v[16:17], v[16:17], v[130:131] op_sel_hi:[1,0]
	v_pk_mul_f32 v[18:19], v[18:19], v[130:131] op_sel_hi:[1,0]
	v_pk_mul_f32 v[108:109], v[108:109], v[116:117]
	v_pk_mul_f32 v[12:13], v[12:13], v[128:129] op_sel_hi:[1,0]
	v_pk_mul_f32 v[104:105], v[104:105], v[108:109]
	v_pk_mul_f32 v[108:109], v[110:111], v[182:183] op_sel_hi:[1,0]
	v_pk_mul_f32 v[8:9], v[8:9], v[128:129] op_sel_hi:[1,0]
	v_pk_mul_f32 v[110:111], v[108:109], s[88:89] op_sel_hi:[1,0]
	v_exp_f32_e32 v110, v110
	v_exp_f32_e32 v111, v111
	v_pk_mul_f32 v[10:11], v[10:11], v[128:129] op_sel_hi:[1,0]
	v_pk_mul_f32 v[4:5], v[4:5], v[128:129] op_sel_hi:[1,0]
	v_pk_add_f32 v[110:111], v[110:111], 1.0 op_sel_hi:[1,0]
	v_rcp_f32_e32 v110, v110
	v_rcp_f32_e32 v111, v111
	v_pk_mul_f32 v[0:1], v[0:1], v[128:129] op_sel_hi:[1,0]
	v_pk_mul_f32 v[2:3], v[2:3], v[128:129] op_sel_hi:[1,0]
	s_andn2_b64 vcc, exec, s[6:7]
	v_pk_mul_f32 v[108:109], v[108:109], v[110:111]
	s_nop 0
	v_pk_mul_f32 v[106:107], v[106:107], v[108:109]
	v_pk_mul_f32 v[108:109], v[100:101], s[88:89] op_sel_hi:[1,0]
	v_exp_f32_e32 v108, v108
	v_exp_f32_e32 v109, v109
	s_nop 0
	v_pk_add_f32 v[108:109], v[108:109], 1.0 op_sel_hi:[1,0]
	v_rcp_f32_e32 v108, v108
	v_rcp_f32_e32 v109, v109
	s_nop 0
	v_pk_mul_f32 v[100:101], v[100:101], v[108:109]
	s_nop 0
	v_pk_mul_f32 v[100:101], v[96:97], v[100:101]
	v_pk_mul_f32 v[96:97], v[102:103], v[182:183] op_sel_hi:[1,0]
	s_nop 0
	v_pk_mul_f32 v[102:103], v[96:97], s[88:89] op_sel_hi:[1,0]
	v_exp_f32_e32 v102, v102
	v_exp_f32_e32 v103, v103
	s_nop 0
	v_pk_add_f32 v[102:103], v[102:103], 1.0 op_sel_hi:[1,0]
	v_rcp_f32_e32 v102, v102
	v_rcp_f32_e32 v103, v103
	s_nop 0
	v_pk_mul_f32 v[96:97], v[96:97], v[102:103]
	s_nop 0
	v_pk_mul_f32 v[102:103], v[98:99], v[96:97]
	v_cvt_pk_bf16_f32 v98, v100, v101
	v_mad_i64_i32 v[100:101], s[8:9], v176, s3, v[112:113]
	v_cvt_pk_bf16_f32 v96, v104, v105
	v_cvt_pk_bf16_f32 v97, v106, v107
	v_cvt_pk_bf16_f32 v99, v102, v103
	v_lshl_add_u64 v[100:101], v[100:101], 0, v[114:115]
	global_store_dwordx4 v[100:101], v[96:99], off
	s_nop 1
	v_pk_mul_f32 v[96:97], v[92:93], s[88:89] op_sel_hi:[1,0]
	v_exp_f32_e32 v96, v96
	v_exp_f32_e32 v97, v97
	s_nop 0
	v_pk_add_f32 v[96:97], v[96:97], 1.0 op_sel_hi:[1,0]
	v_rcp_f32_e32 v96, v96
	v_rcp_f32_e32 v97, v97
	s_nop 0
	v_pk_mul_f32 v[92:93], v[92:93], v[96:97]
	s_nop 0
	v_pk_mul_f32 v[88:89], v[88:89], v[92:93]
	v_pk_mul_f32 v[92:93], v[94:95], v[146:147] op_sel_hi:[1,0]
	s_nop 0
	v_pk_mul_f32 v[94:95], v[92:93], s[88:89] op_sel_hi:[1,0]
	v_exp_f32_e32 v94, v94
	v_exp_f32_e32 v95, v95
	s_nop 0
	v_pk_add_f32 v[94:95], v[94:95], 1.0 op_sel_hi:[1,0]
	v_rcp_f32_e32 v94, v94
	v_rcp_f32_e32 v95, v95
	s_nop 0
	v_pk_mul_f32 v[92:93], v[92:93], v[94:95]
	s_nop 0
	v_pk_mul_f32 v[90:91], v[90:91], v[92:93]
	v_pk_mul_f32 v[92:93], v[84:85], s[88:89] op_sel_hi:[1,0]
	v_exp_f32_e32 v92, v92
	v_exp_f32_e32 v93, v93
	s_nop 0
	v_pk_add_f32 v[92:93], v[92:93], 1.0 op_sel_hi:[1,0]
	v_rcp_f32_e32 v92, v92
	v_rcp_f32_e32 v93, v93
	s_nop 0
	v_pk_mul_f32 v[84:85], v[84:85], v[92:93]
	s_nop 0
	v_pk_mul_f32 v[84:85], v[80:81], v[84:85]
	v_pk_mul_f32 v[80:81], v[86:87], v[146:147] op_sel_hi:[1,0]
	s_nop 0
	v_pk_mul_f32 v[86:87], v[80:81], s[88:89] op_sel_hi:[1,0]
	v_exp_f32_e32 v86, v86
	v_exp_f32_e32 v87, v87
	s_nop 0
	v_pk_add_f32 v[86:87], v[86:87], 1.0 op_sel_hi:[1,0]
	v_rcp_f32_e32 v86, v86
	v_rcp_f32_e32 v87, v87
	s_nop 0
	v_pk_mul_f32 v[80:81], v[80:81], v[86:87]
	s_nop 0
	v_pk_mul_f32 v[86:87], v[82:83], v[80:81]
	v_cvt_pk_bf16_f32 v82, v84, v85
	v_mad_i64_i32 v[84:85], s[8:9], v174, s3, v[112:113]
	v_cvt_pk_bf16_f32 v80, v88, v89
	v_cvt_pk_bf16_f32 v81, v90, v91
	v_cvt_pk_bf16_f32 v83, v86, v87
	v_lshl_add_u64 v[84:85], v[84:85], 0, v[114:115]
	global_store_dwordx4 v[84:85], v[80:83], off
	s_nop 1
	v_pk_mul_f32 v[80:81], v[76:77], s[88:89] op_sel_hi:[1,0]
	v_exp_f32_e32 v80, v80
	v_exp_f32_e32 v81, v81
	s_nop 0
	v_pk_add_f32 v[80:81], v[80:81], 1.0 op_sel_hi:[1,0]
	v_rcp_f32_e32 v80, v80
	v_rcp_f32_e32 v81, v81
	s_nop 0
	v_pk_mul_f32 v[76:77], v[76:77], v[80:81]
	s_nop 0
	v_pk_mul_f32 v[72:73], v[72:73], v[76:77]
	v_pk_mul_f32 v[76:77], v[78:79], v[144:145] op_sel_hi:[1,0]
	s_nop 0
	v_pk_mul_f32 v[78:79], v[76:77], s[88:89] op_sel_hi:[1,0]
	v_exp_f32_e32 v78, v78
	v_exp_f32_e32 v79, v79
	s_nop 0
	v_pk_add_f32 v[78:79], v[78:79], 1.0 op_sel_hi:[1,0]
	v_rcp_f32_e32 v78, v78
	v_rcp_f32_e32 v79, v79
	s_nop 0
	v_pk_mul_f32 v[76:77], v[76:77], v[78:79]
	s_nop 0
	v_pk_mul_f32 v[74:75], v[74:75], v[76:77]
	v_pk_mul_f32 v[76:77], v[68:69], s[88:89] op_sel_hi:[1,0]
	v_exp_f32_e32 v76, v76
	v_exp_f32_e32 v77, v77
	s_nop 0
	v_pk_add_f32 v[76:77], v[76:77], 1.0 op_sel_hi:[1,0]
	v_rcp_f32_e32 v76, v76
	v_rcp_f32_e32 v77, v77
	s_nop 0
	v_pk_mul_f32 v[68:69], v[68:69], v[76:77]
	s_nop 0
	v_pk_mul_f32 v[68:69], v[64:65], v[68:69]
	v_pk_mul_f32 v[64:65], v[70:71], v[144:145] op_sel_hi:[1,0]
	s_nop 0
	v_pk_mul_f32 v[70:71], v[64:65], s[88:89] op_sel_hi:[1,0]
	v_exp_f32_e32 v70, v70
	v_exp_f32_e32 v71, v71
	s_nop 0
	v_pk_add_f32 v[70:71], v[70:71], 1.0 op_sel_hi:[1,0]
	v_rcp_f32_e32 v70, v70
	v_rcp_f32_e32 v71, v71
	s_nop 0
	v_pk_mul_f32 v[64:65], v[64:65], v[70:71]
	s_nop 0
	v_pk_mul_f32 v[70:71], v[66:67], v[64:65]
	v_cvt_pk_bf16_f32 v66, v68, v69
	v_mad_i64_i32 v[68:69], s[8:9], v172, s3, v[112:113]
	v_cvt_pk_bf16_f32 v64, v72, v73
	v_cvt_pk_bf16_f32 v65, v74, v75
	v_cvt_pk_bf16_f32 v67, v70, v71
	v_lshl_add_u64 v[68:69], v[68:69], 0, v[114:115]
	global_store_dwordx4 v[68:69], v[64:67], off
	s_nop 1
	v_pk_mul_f32 v[64:65], v[60:61], s[88:89] op_sel_hi:[1,0]
	v_exp_f32_e32 v64, v64
	v_exp_f32_e32 v65, v65
	s_nop 0
	v_pk_add_f32 v[64:65], v[64:65], 1.0 op_sel_hi:[1,0]
	v_rcp_f32_e32 v64, v64
	v_rcp_f32_e32 v65, v65
	s_nop 0
	v_pk_mul_f32 v[60:61], v[60:61], v[64:65]
	s_nop 0
	v_pk_mul_f32 v[56:57], v[56:57], v[60:61]
	v_pk_mul_f32 v[60:61], v[62:63], v[138:139] op_sel_hi:[1,0]
	s_nop 0
	v_pk_mul_f32 v[62:63], v[60:61], s[88:89] op_sel_hi:[1,0]
	v_exp_f32_e32 v62, v62
	v_exp_f32_e32 v63, v63
	s_nop 0
	v_pk_add_f32 v[62:63], v[62:63], 1.0 op_sel_hi:[1,0]
	v_rcp_f32_e32 v62, v62
	v_rcp_f32_e32 v63, v63
	s_nop 0
	v_pk_mul_f32 v[60:61], v[60:61], v[62:63]
	s_nop 0
	v_pk_mul_f32 v[58:59], v[58:59], v[60:61]
	v_pk_mul_f32 v[60:61], v[52:53], s[88:89] op_sel_hi:[1,0]
	v_exp_f32_e32 v60, v60
	v_exp_f32_e32 v61, v61
	s_nop 0
	v_pk_add_f32 v[60:61], v[60:61], 1.0 op_sel_hi:[1,0]
	v_rcp_f32_e32 v60, v60
	v_rcp_f32_e32 v61, v61
	s_nop 0
	v_pk_mul_f32 v[52:53], v[52:53], v[60:61]
	s_nop 0
	v_pk_mul_f32 v[52:53], v[48:49], v[52:53]
	v_pk_mul_f32 v[48:49], v[54:55], v[138:139] op_sel_hi:[1,0]
	s_nop 0
	v_pk_mul_f32 v[54:55], v[48:49], s[88:89] op_sel_hi:[1,0]
	v_exp_f32_e32 v54, v54
	v_exp_f32_e32 v55, v55
	s_nop 0
	v_pk_add_f32 v[54:55], v[54:55], 1.0 op_sel_hi:[1,0]
	v_rcp_f32_e32 v54, v54
	v_rcp_f32_e32 v55, v55
	s_nop 0
	v_pk_mul_f32 v[48:49], v[48:49], v[54:55]
	s_nop 0
	v_pk_mul_f32 v[54:55], v[50:51], v[48:49]
	v_cvt_pk_bf16_f32 v50, v52, v53
	v_mad_i64_i32 v[52:53], s[8:9], v170, s3, v[112:113]
	v_cvt_pk_bf16_f32 v48, v56, v57
	v_cvt_pk_bf16_f32 v49, v58, v59
	v_cvt_pk_bf16_f32 v51, v54, v55
	v_lshl_add_u64 v[52:53], v[52:53], 0, v[114:115]
	global_store_dwordx4 v[52:53], v[48:51], off
	s_nop 1
	v_pk_mul_f32 v[48:49], v[44:45], s[88:89] op_sel_hi:[1,0]
	v_exp_f32_e32 v48, v48
	v_exp_f32_e32 v49, v49
	s_nop 0
	v_pk_add_f32 v[48:49], v[48:49], 1.0 op_sel_hi:[1,0]
	v_rcp_f32_e32 v48, v48
	v_rcp_f32_e32 v49, v49
	s_nop 0
	v_pk_mul_f32 v[44:45], v[44:45], v[48:49]
	s_nop 0
	v_pk_mul_f32 v[40:41], v[40:41], v[44:45]
	v_pk_mul_f32 v[44:45], v[46:47], v[136:137] op_sel_hi:[1,0]
	s_nop 0
	v_pk_mul_f32 v[46:47], v[44:45], s[88:89] op_sel_hi:[1,0]
	v_exp_f32_e32 v46, v46
	v_exp_f32_e32 v47, v47
	s_nop 0
	v_pk_add_f32 v[46:47], v[46:47], 1.0 op_sel_hi:[1,0]
	v_rcp_f32_e32 v46, v46
	v_rcp_f32_e32 v47, v47
	s_nop 0
	v_pk_mul_f32 v[44:45], v[44:45], v[46:47]
	s_nop 0
	v_pk_mul_f32 v[42:43], v[42:43], v[44:45]
	v_pk_mul_f32 v[44:45], v[36:37], s[88:89] op_sel_hi:[1,0]
	v_exp_f32_e32 v44, v44
	v_exp_f32_e32 v45, v45
	s_nop 0
	v_pk_add_f32 v[44:45], v[44:45], 1.0 op_sel_hi:[1,0]
	v_rcp_f32_e32 v44, v44
	v_rcp_f32_e32 v45, v45
	s_nop 0
	v_pk_mul_f32 v[36:37], v[36:37], v[44:45]
	s_nop 0
	v_pk_mul_f32 v[36:37], v[32:33], v[36:37]
	v_pk_mul_f32 v[32:33], v[38:39], v[136:137] op_sel_hi:[1,0]
	s_nop 0
	v_pk_mul_f32 v[38:39], v[32:33], s[88:89] op_sel_hi:[1,0]
	v_exp_f32_e32 v38, v38
	v_exp_f32_e32 v39, v39
	s_nop 0
	v_pk_add_f32 v[38:39], v[38:39], 1.0 op_sel_hi:[1,0]
	v_rcp_f32_e32 v38, v38
	v_rcp_f32_e32 v39, v39
	s_nop 0
	v_pk_mul_f32 v[32:33], v[32:33], v[38:39]
	s_nop 0
	v_pk_mul_f32 v[38:39], v[34:35], v[32:33]
	v_cvt_pk_bf16_f32 v34, v36, v37
	v_mad_i64_i32 v[36:37], s[8:9], v168, s3, v[112:113]
	v_cvt_pk_bf16_f32 v32, v40, v41
	v_cvt_pk_bf16_f32 v33, v42, v43
	v_cvt_pk_bf16_f32 v35, v38, v39
	v_lshl_add_u64 v[36:37], v[36:37], 0, v[114:115]
	global_store_dwordx4 v[36:37], v[32:35], off
	s_nop 1
	v_pk_mul_f32 v[32:33], v[28:29], s[88:89] op_sel_hi:[1,0]
	v_exp_f32_e32 v32, v32
	v_exp_f32_e32 v33, v33
	s_nop 0
	v_pk_add_f32 v[32:33], v[32:33], 1.0 op_sel_hi:[1,0]
	v_rcp_f32_e32 v32, v32
	v_rcp_f32_e32 v33, v33
	s_nop 0
	v_pk_mul_f32 v[28:29], v[28:29], v[32:33]
	s_nop 0
	v_pk_mul_f32 v[24:25], v[24:25], v[28:29]
	v_pk_mul_f32 v[28:29], v[30:31], v[130:131] op_sel_hi:[1,0]
	s_nop 0
	v_pk_mul_f32 v[30:31], v[28:29], s[88:89] op_sel_hi:[1,0]
	v_exp_f32_e32 v30, v30
	v_exp_f32_e32 v31, v31
	s_nop 0
	v_pk_add_f32 v[30:31], v[30:31], 1.0 op_sel_hi:[1,0]
	v_rcp_f32_e32 v30, v30
	v_rcp_f32_e32 v31, v31
	s_nop 0
	v_pk_mul_f32 v[28:29], v[28:29], v[30:31]
	s_nop 0
	v_pk_mul_f32 v[26:27], v[26:27], v[28:29]
	v_pk_mul_f32 v[28:29], v[20:21], s[88:89] op_sel_hi:[1,0]
	v_exp_f32_e32 v28, v28
	v_exp_f32_e32 v29, v29
	s_nop 0
	v_pk_add_f32 v[28:29], v[28:29], 1.0 op_sel_hi:[1,0]
	v_rcp_f32_e32 v28, v28
	v_rcp_f32_e32 v29, v29
	s_nop 0
	v_pk_mul_f32 v[20:21], v[20:21], v[28:29]
	s_nop 0
	v_pk_mul_f32 v[20:21], v[16:17], v[20:21]
	v_pk_mul_f32 v[16:17], v[22:23], v[130:131] op_sel_hi:[1,0]
	s_nop 0
	v_pk_mul_f32 v[22:23], v[16:17], s[88:89] op_sel_hi:[1,0]
	v_exp_f32_e32 v22, v22
	v_exp_f32_e32 v23, v23
	s_nop 0
	v_pk_add_f32 v[22:23], v[22:23], 1.0 op_sel_hi:[1,0]
	v_rcp_f32_e32 v22, v22
	v_rcp_f32_e32 v23, v23
	s_nop 0
	v_pk_mul_f32 v[16:17], v[16:17], v[22:23]
	s_nop 0
	v_pk_mul_f32 v[22:23], v[18:19], v[16:17]
	v_cvt_pk_bf16_f32 v18, v20, v21
	v_mad_i64_i32 v[20:21], s[8:9], v166, s3, v[112:113]
	v_cvt_pk_bf16_f32 v16, v24, v25
	v_cvt_pk_bf16_f32 v17, v26, v27
	v_cvt_pk_bf16_f32 v19, v22, v23
	v_lshl_add_u64 v[20:21], v[20:21], 0, v[114:115]
	global_store_dwordx4 v[20:21], v[16:19], off
	s_nop 1
	v_pk_mul_f32 v[16:17], v[12:13], s[88:89] op_sel_hi:[1,0]
	v_exp_f32_e32 v16, v16
	v_exp_f32_e32 v17, v17
	s_nop 0
	v_pk_add_f32 v[16:17], v[16:17], 1.0 op_sel_hi:[1,0]
	v_rcp_f32_e32 v16, v16
	v_rcp_f32_e32 v17, v17
	s_nop 0
	v_pk_mul_f32 v[12:13], v[12:13], v[16:17]
	s_nop 0
	v_pk_mul_f32 v[8:9], v[8:9], v[12:13]
	v_pk_mul_f32 v[12:13], v[14:15], v[128:129] op_sel_hi:[1,0]
	s_nop 0
	v_pk_mul_f32 v[14:15], v[12:13], s[88:89] op_sel_hi:[1,0]
	v_exp_f32_e32 v14, v14
	v_exp_f32_e32 v15, v15
	s_nop 0
	v_pk_add_f32 v[14:15], v[14:15], 1.0 op_sel_hi:[1,0]
	v_rcp_f32_e32 v14, v14
	v_rcp_f32_e32 v15, v15
	s_nop 0
	v_pk_mul_f32 v[12:13], v[12:13], v[14:15]
	s_nop 0
	v_pk_mul_f32 v[10:11], v[10:11], v[12:13]
	v_pk_mul_f32 v[12:13], v[4:5], s[88:89] op_sel_hi:[1,0]
	v_exp_f32_e32 v12, v12
	v_exp_f32_e32 v13, v13
	s_nop 0
	v_pk_add_f32 v[12:13], v[12:13], 1.0 op_sel_hi:[1,0]
	v_rcp_f32_e32 v12, v12
	v_rcp_f32_e32 v13, v13
	s_nop 0
	v_pk_mul_f32 v[4:5], v[4:5], v[12:13]
	s_nop 0
	v_pk_mul_f32 v[4:5], v[0:1], v[4:5]
	v_pk_mul_f32 v[0:1], v[6:7], v[128:129] op_sel_hi:[1,0]
	s_nop 0
	v_pk_mul_f32 v[6:7], v[0:1], s[88:89] op_sel_hi:[1,0]
	v_exp_f32_e32 v6, v6
	v_exp_f32_e32 v7, v7
	s_nop 0
	v_pk_add_f32 v[6:7], v[6:7], 1.0 op_sel_hi:[1,0]
	v_rcp_f32_e32 v6, v6
	v_rcp_f32_e32 v7, v7
	s_nop 0
	v_pk_mul_f32 v[0:1], v[0:1], v[6:7]
	s_nop 0
	v_pk_mul_f32 v[6:7], v[2:3], v[0:1]
	v_cvt_pk_bf16_f32 v2, v4, v5
	v_mad_i64_i32 v[4:5], s[8:9], v164, s3, v[112:113]
	v_cvt_pk_bf16_f32 v0, v8, v9
	v_cvt_pk_bf16_f32 v1, v10, v11
	v_cvt_pk_bf16_f32 v3, v6, v7
	v_lshl_add_u64 v[4:5], v[4:5], 0, v[114:115]
	s_mov_b64 s[8:9], -1
	global_store_dwordx4 v[4:5], v[0:3], off
	s_cbranch_vccnz .LBB0_931
	s_andn2_b64 vcc, exec, s[10:11]
	s_cbranch_vccnz .LBB0_930
	s_barrier
	s_branch .LBB0_930
